# P2 item epilogues: compress-1 bias quads loaded once (was 16 serialized reloads), MLA q up-projection rope rows requested four at a time with counted waits (was 16 serialized load+drain round trips pe
# speedup vs baseline: 1.0065x; 1.0065x over previous
; DEVI void store_bf4(bf16_t* p, f32x4 v) { u32x2 w; w.x = pk2(v[0], v[1]); w.y = pk2(v[2], v[3]); *(u32x2*)p = w; }
; template <bool ROWSS, class AD, class Epi>
; DEVI void gemm_tile(const AD& ad, const bf16_t* __restrict__ Bt, int K, int m0, int n0, const Epi& epi, unsigned char* lds, int wv) {
;     ...
;     for (int i = 0; i < 4; ++i) rs[i] = rsl[wm * 64 + i * 16 + idx];
;   }
; #pragma unroll
;   for (int j = 0; j < 4; ++j) {
;     const int n = n0 + wn * 64 + j * 16 + quad * 4;
; #pragma unroll
;     for (int i = 0; i < 4; ++i) epi(m0 + wm * 64 + i * 16 + idx, n, acc[i][j], rs[i]);
;   DEVI void operator()(int m, int n, f32x4 v, float rs) const {
;     if (n >= 480) return;
;     v *= rs;
;     int d = n % 96;
;     if (d >= 64) {
;       const float4 cs = *(const float4*)(rope + ((size_t)m * 56 + 8 + ((d - 64) >> 1)) * 2);
;       float a0 = v[0] * cs.x - v[1] * cs.y, a1 = v[1] * cs.x + v[0] * cs.y;
;       float a2 = v[2] * cs.z - v[3] * cs.w, a3 = v[3] * cs.z + v[2] * cs.w;
;       v = (f32x4){a0, a1, a2, a3};
;     }
;     v *= QSCALE_MLA;
;     store_bf4(qm + (size_t)m * 512 + n, v);
.LBB0_864:
	s_or_b64 exec, exec, s[0:1]
	v_lshl_add_u32 v32, v112, 2, 0
	v_add_u32_e32 v32, 0x1b000, v32
	s_waitcnt lgkmcnt(0)
	s_barrier
	s_waitcnt vmcnt(3)
	ds_read2_b32 v[66:67], v32 offset1:16
	ds_read2_b32 v[60:61], v32 offset0:32 offset1:48
	v_lshlrev_b32_e32 v32, 2, v109
	s_waitcnt vmcnt(0)
	v_or3_b32 v78, v32, s3, v110
	v_or_b32_e32 v32, s2, v108
	s_mov_b32 s0, 0x2aaaaab
	v_add_u32_e32 v64, v111, v32
	v_mul_hi_u32 v32, v78, s0
	v_mul_u32_u24_e32 v32, 0x60, v32
	v_sub_u32_e32 v32, v78, v32
	v_cmp_lt_u32_e32 vcc, 63, v32
	v_subrev_u32_e32 v32, 64, v32
	v_lshrrev_b32_e32 v32, 1, v32
	s_waitcnt lgkmcnt(1)
	v_mov_b32_e32 v62, v67
	s_waitcnt lgkmcnt(0)
	v_mov_b32_e32 v58, v61
	v_add_u32_e32 v32, 8, v32
	v_pk_mul_f32 v[70:71], v[88:89], v[66:67] op_sel_hi:[1,0]
	v_pk_mul_f32 v[68:69], v[86:87], v[66:67] op_sel_hi:[1,0]
	v_ashrrev_i32_e32 v65, 31, v64
	s_and_saveexec_b64 s[0:1], vcc
	v_readlane_b32 s2, v252, 63
	v_readlane_b32 s3, v253, 0
	v_mov_b32_e32 v198, v64
	v_mad_u32_u24 v198, v198, 56, v32
	v_lshlrev_b32_e32 v198, 3, v198
	v_or_b32_e32 v199, 16, v64
	v_mad_u32_u24 v199, v199, 56, v32
	v_lshlrev_b32_e32 v199, 3, v199
	v_or_b32_e32 v200, 32, v64
	v_mad_u32_u24 v200, v200, 56, v32
	v_lshlrev_b32_e32 v200, 3, v200
	v_or_b32_e32 v201, 48, v64
	v_mad_u32_u24 v201, v201, 56, v32
	v_lshlrev_b32_e32 v201, 3, v201
	global_load_dwordx4 v[182:185], v198, s[2:3]
	global_load_dwordx4 v[186:189], v199, s[2:3]
	global_load_dwordx4 v[190:193], v200, s[2:3]
	global_load_dwordx4 v[194:197], v201, s[2:3]
	s_or_b64 exec, exec, s[0:1]
	s_and_saveexec_b64 s[0:1], vcc
	s_cbranch_execz .LBB0_866
	s_waitcnt vmcnt(3)
	v_mov_b32_e32 v72, v182
	v_mov_b32_e32 v73, v183
	v_mov_b32_e32 v74, v184
	v_mov_b32_e32 v75, v185
	v_pk_mul_f32 v[80:81], v[68:69], v[72:73] op_sel:[1,1] op_sel_hi:[0,1]
	v_pk_mul_f32 v[76:77], v[68:69], v[72:73] op_sel_hi:[1,0]
	v_pk_fma_f32 v[68:69], v[68:69], v[72:73], v[80:81] op_sel_hi:[1,0,1]
	s_nop 0
	v_mul_f32_e32 v68, v71, v75
	v_pk_fma_f32 v[72:73], v[70:71], v[74:75], v[68:69] op_sel_hi:[1,1,0] neg_lo:[0,0,1] neg_hi:[0,0,1]
	v_mul_f32_e32 v68, v70, v75
	v_pk_fma_f32 v[74:75], v[70:71], v[74:75], v[68:69] op_sel:[1,0,0] op_sel_hi:[0,1,0]
	v_sub_f32_e32 v68, v76, v80
	v_mov_b32_e32 v70, v72
	v_mov_b32_e32 v71, v74
.LBB0_866:
	s_or_b64 exec, exec, s[0:1]
	v_readlane_b32 s0, v253, 26
	v_lshlrev_b32_e32 v72, 1, v78
	v_mov_b32_e32 v73, v33
	v_readlane_b32 s1, v253, 27
	v_lshlrev_b64 v[74:75], 10, v[64:65]
	s_nop 0
	v_lshl_add_u64 v[76:77], s[0:1], 0, v[72:73]
	s_mov_b32 s0, 0x3e16c740
	v_pk_mul_f32 v[68:69], v[68:69], s[0:1] op_sel_hi:[1,0]
	v_lshl_add_u64 v[72:73], v[76:77], 0, v[74:75]
	v_cvt_pk_bf16_f32 v68, v68, v69
	v_pk_mul_f32 v[70:71], v[70:71], s[0:1] op_sel_hi:[1,0]
	s_nop 0
	v_cvt_pk_bf16_f32 v69, v70, v71
	global_store_dwordx2 v[72:73], v[68:69], off
	v_or_b32_e32 v68, 16, v64
	v_pk_mul_f32 v[72:73], v[84:85], v[62:63] op_sel_hi:[1,0]
	v_pk_mul_f32 v[70:71], v[82:83], v[62:63] op_sel_hi:[1,0]
	v_ashrrev_i32_e32 v69, 31, v68
	s_and_saveexec_b64 s[0:1], vcc
	s_cbranch_execz .LBB0_868
	s_waitcnt vmcnt(3)
	v_mov_b32_e32 v80, v186
	v_mov_b32_e32 v81, v187
	v_mov_b32_e32 v82, v188
	v_mov_b32_e32 v83, v189
	v_pk_mul_f32 v[86:87], v[70:71], v[80:81] op_sel:[1,1] op_sel_hi:[0,1]
	v_pk_mul_f32 v[84:85], v[70:71], v[80:81] op_sel_hi:[1,0]
	v_pk_fma_f32 v[70:71], v[70:71], v[80:81], v[86:87] op_sel_hi:[1,0,1]
	s_nop 0
	v_mul_f32_e32 v70, v73, v83
	v_pk_fma_f32 v[80:81], v[72:73], v[82:83], v[70:71] op_sel_hi:[1,1,0] neg_lo:[0,0,1] neg_hi:[0,0,1]
	v_mul_f32_e32 v70, v72, v83
	v_pk_fma_f32 v[82:83], v[72:73], v[82:83], v[70:71] op_sel:[1,0,0] op_sel_hi:[0,1,0]
	v_sub_f32_e32 v70, v84, v86
	v_mov_b32_e32 v72, v80
	v_mov_b32_e32 v73, v82
.LBB0_868:
	s_or_b64 exec, exec, s[0:1]
	s_mov_b32 s0, 0x3e16c740
	v_pk_mul_f32 v[80:81], v[72:73], s[0:1] op_sel_hi:[1,0]
	v_pk_mul_f32 v[70:71], v[70:71], s[0:1] op_sel_hi:[1,0]
	v_lshlrev_b64 v[72:73], 10, v[68:69]
	v_lshl_add_u64 v[82:83], v[76:77], 0, v[72:73]
	v_cvt_pk_bf16_f32 v70, v70, v71
	v_cvt_pk_bf16_f32 v71, v80, v81
	global_store_dwordx2 v[82:83], v[70:71], off
	v_or_b32_e32 v70, 32, v64
	v_pk_mul_f32 v[56:57], v[56:57], v[60:61] op_sel_hi:[1,0]
	v_pk_mul_f32 v[54:55], v[54:55], v[60:61] op_sel_hi:[1,0]
	v_ashrrev_i32_e32 v71, 31, v70
	s_and_saveexec_b64 s[0:1], vcc
	s_cbranch_execz .LBB0_870
	s_waitcnt vmcnt(3)
	v_mov_b32_e32 v80, v190
	v_mov_b32_e32 v81, v191
	v_mov_b32_e32 v82, v192
	v_mov_b32_e32 v83, v193
	v_pk_mul_f32 v[86:87], v[54:55], v[80:81] op_sel:[1,1] op_sel_hi:[0,1]
	v_pk_mul_f32 v[84:85], v[54:55], v[80:81] op_sel_hi:[1,0]
	v_pk_fma_f32 v[54:55], v[54:55], v[80:81], v[86:87] op_sel_hi:[1,0,1]
	s_nop 0
	v_mul_f32_e32 v54, v57, v83
	v_pk_fma_f32 v[80:81], v[56:57], v[82:83], v[54:55] op_sel_hi:[1,1,0] neg_lo:[0,0,1] neg_hi:[0,0,1]
	v_mul_f32_e32 v54, v56, v83
	v_pk_fma_f32 v[82:83], v[56:57], v[82:83], v[54:55] op_sel:[1,0,0] op_sel_hi:[0,1,0]
	v_sub_f32_e32 v54, v84, v86
	v_mov_b32_e32 v56, v80
	v_mov_b32_e32 v57, v82
.LBB0_870:
	s_or_b64 exec, exec, s[0:1]
	s_mov_b32 s0, 0x3e16c740
	v_pk_mul_f32 v[80:81], v[56:57], s[0:1] op_sel_hi:[1,0]
	v_pk_mul_f32 v[54:55], v[54:55], s[0:1] op_sel_hi:[1,0]
	v_lshlrev_b64 v[56:57], 10, v[70:71]
	v_lshl_add_u64 v[82:83], v[76:77], 0, v[56:57]
	v_cvt_pk_bf16_f32 v54, v54, v55
	v_cvt_pk_bf16_f32 v55, v80, v81
	global_store_dwordx2 v[82:83], v[54:55], off
	v_or_b32_e32 v54, 48, v64
	v_pk_mul_f32 v[52:53], v[52:53], v[58:59] op_sel_hi:[1,0]
	v_pk_mul_f32 v[50:51], v[50:51], v[58:59] op_sel_hi:[1,0]
	v_ashrrev_i32_e32 v55, 31, v54
	s_and_saveexec_b64 s[0:1], vcc
	s_cbranch_execz .LBB0_872
	s_waitcnt vmcnt(3)
	v_mov_b32_e32 v80, v194
	v_mov_b32_e32 v81, v195
	v_mov_b32_e32 v82, v196
	v_mov_b32_e32 v83, v197
	v_pk_mul_f32 v[86:87], v[50:51], v[80:81] op_sel:[1,1] op_sel_hi:[0,1]
	v_mul_f32_e32 v32, v53, v83
	v_pk_mul_f32 v[84:85], v[50:51], v[80:81] op_sel_hi:[1,0]
	v_pk_fma_f32 v[50:51], v[50:51], v[80:81], v[86:87] op_sel_hi:[1,0,1]
	v_pk_fma_f32 v[80:81], v[52:53], v[82:83], v[32:33] op_sel_hi:[1,1,0] neg_lo:[0,0,1] neg_hi:[0,0,1]
	v_mul_f32_e32 v32, v52, v83
	v_pk_fma_f32 v[82:83], v[52:53], v[82:83], v[32:33] op_sel:[1,0,0] op_sel_hi:[0,1,0]
	v_sub_f32_e32 v50, v84, v86
	v_mov_b32_e32 v52, v80
	v_mov_b32_e32 v53, v82
; DEVI void store_bf4(bf16_t* p, f32x4 v) { u32x2 w; w.x = pk2(v[0], v[1]); w.y = pk2(v[2], v[3]); *(u32x2*)p = w; }
;   DEVI void operator()(int m, int n, f32x4 v, float rs) const {
;     if (n >= 480) return;
;     v *= rs;
;     int d = n % 96;
;     if (d >= 64) {
;       const float4 cs = *(const float4*)(rope + ((size_t)m * 56 + 8 + ((d - 64) >> 1)) * 2);
;       float a0 = v[0] * cs.x - v[1] * cs.y, a1 = v[1] * cs.x + v[0] * cs.y;
;       float a2 = v[2] * cs.z - v[3] * cs.w, a3 = v[3] * cs.z + v[2] * cs.w;
;       v = (f32x4){a0, a1, a2, a3};
;     }
;     v *= QSCALE_MLA;
;     store_bf4(qm + (size_t)m * 512 + n, v);
.LBB0_872:
	s_or_b64 exec, exec, s[0:1]
	s_mov_b32 s0, 0x3e16c740
	v_pk_mul_f32 v[52:53], v[52:53], s[0:1] op_sel_hi:[1,0]
	v_pk_mul_f32 v[80:81], v[50:51], s[0:1] op_sel_hi:[1,0]
	s_mov_b32 s0, 0x2aaaaab
	v_cvt_pk_bf16_f32 v80, v80, v81
	v_cvt_pk_bf16_f32 v81, v52, v53
	v_or_b32_e32 v52, 16, v78
	v_mul_hi_u32 v32, v52, s0
	v_mul_u32_u24_e32 v32, 0x60, v32
	v_lshlrev_b64 v[50:51], 10, v[54:55]
	v_sub_u32_e32 v32, v52, v32
	v_lshl_add_u64 v[76:77], v[76:77], 0, v[50:51]
	v_cmp_lt_u32_e32 vcc, 63, v32
	v_subrev_u32_e32 v32, 64, v32
	v_mov_b32_e32 v67, v66
	global_store_dwordx2 v[76:77], v[80:81], off
	v_lshrrev_b32_e32 v32, 1, v32
	v_mov_b32_e32 v76, v66
	v_mov_b32_e32 v77, v66
	v_add_u32_e32 v32, 8, v32
	v_pk_mul_f32 v[48:49], v[48:49], v[76:77]
	v_pk_mul_f32 v[46:47], v[46:47], v[66:67]
	s_and_saveexec_b64 s[0:1], vcc
	v_readlane_b32 s2, v252, 63
	v_readlane_b32 s3, v253, 0
	v_mov_b32_e32 v198, v64
	v_mad_u32_u24 v198, v198, 56, v32
	v_lshlrev_b32_e32 v198, 3, v198
	v_or_b32_e32 v199, 16, v64
	v_mad_u32_u24 v199, v199, 56, v32
	v_lshlrev_b32_e32 v199, 3, v199
	v_or_b32_e32 v200, 32, v64
	v_mad_u32_u24 v200, v200, 56, v32
	v_lshlrev_b32_e32 v200, 3, v200
	v_or_b32_e32 v201, 48, v64
	v_mad_u32_u24 v201, v201, 56, v32
	v_lshlrev_b32_e32 v201, 3, v201
	global_load_dwordx4 v[182:185], v198, s[2:3]
	global_load_dwordx4 v[186:189], v199, s[2:3]
	global_load_dwordx4 v[190:193], v200, s[2:3]
	global_load_dwordx4 v[194:197], v201, s[2:3]
	s_or_b64 exec, exec, s[0:1]
	s_and_saveexec_b64 s[0:1], vcc
	s_cbranch_execz .LBB0_874
	s_waitcnt vmcnt(3)
	v_mov_b32_e32 v80, v182
	v_mov_b32_e32 v81, v183
	v_mov_b32_e32 v82, v184
	v_mov_b32_e32 v83, v185
	v_pk_mul_f32 v[84:85], v[46:47], v[80:81] op_sel:[1,1] op_sel_hi:[0,1]
	v_pk_mul_f32 v[76:77], v[46:47], v[80:81] op_sel_hi:[1,0]
	v_pk_fma_f32 v[46:47], v[46:47], v[80:81], v[84:85] op_sel_hi:[1,0,1]
	s_nop 0
	v_mul_f32_e32 v46, v49, v83
	v_pk_fma_f32 v[80:81], v[48:49], v[82:83], v[46:47] op_sel_hi:[1,1,0] neg_lo:[0,0,1] neg_hi:[0,0,1]
	v_mul_f32_e32 v46, v48, v83
	v_pk_fma_f32 v[82:83], v[48:49], v[82:83], v[46:47] op_sel:[1,0,0] op_sel_hi:[0,1,0]
	v_sub_f32_e32 v46, v76, v84
	v_mov_b32_e32 v48, v80
	v_mov_b32_e32 v49, v82
.LBB0_874:
	s_or_b64 exec, exec, s[0:1]
	s_mov_b32 s0, 0x3e16c740
	v_pk_mul_f32 v[76:77], v[48:49], s[0:1] op_sel_hi:[1,0]
	v_pk_mul_f32 v[80:81], v[46:47], s[0:1] op_sel_hi:[1,0]
	v_readlane_b32 s0, v253, 26
	v_readlane_b32 s1, v253, 27
	v_lshlrev_b32_e32 v48, 1, v52
	v_mov_b32_e32 v49, v33
	v_lshl_add_u64 v[46:47], s[0:1], 0, v[74:75]
	v_lshl_add_u64 v[52:53], v[46:47], 0, v[48:49]
	v_mov_b32_e32 v63, v62
	v_cvt_pk_bf16_f32 v74, v80, v81
	v_cvt_pk_bf16_f32 v75, v76, v77
	global_store_dwordx2 v[52:53], v[74:75], off
	v_mov_b32_e32 v52, v62
	v_mov_b32_e32 v53, v62
	v_pk_mul_f32 v[44:45], v[44:45], v[52:53]
	v_pk_mul_f32 v[42:43], v[42:43], v[62:63]
	s_and_saveexec_b64 s[0:1], vcc
	s_cbranch_execz .LBB0_876
	s_waitcnt vmcnt(3)
	v_mov_b32_e32 v74, v186
	v_mov_b32_e32 v75, v187
	v_mov_b32_e32 v76, v188
	v_mov_b32_e32 v77, v189
	v_pk_mul_f32 v[80:81], v[42:43], v[74:75] op_sel:[1,1] op_sel_hi:[0,1]
	v_pk_mul_f32 v[52:53], v[42:43], v[74:75] op_sel_hi:[1,0]
	v_pk_fma_f32 v[42:43], v[42:43], v[74:75], v[80:81] op_sel_hi:[1,0,1]
	s_nop 0
	v_mul_f32_e32 v42, v45, v77
	v_pk_fma_f32 v[74:75], v[44:45], v[76:77], v[42:43] op_sel_hi:[1,1,0] neg_lo:[0,0,1] neg_hi:[0,0,1]
	v_mul_f32_e32 v42, v44, v77
	v_pk_fma_f32 v[76:77], v[44:45], v[76:77], v[42:43] op_sel:[1,0,0] op_sel_hi:[0,1,0]
	v_sub_f32_e32 v42, v52, v80
	v_mov_b32_e32 v44, v74
	v_mov_b32_e32 v45, v76
.LBB0_876:
	s_or_b64 exec, exec, s[0:1]
	s_mov_b32 s0, 0x3e16c740
	v_pk_mul_f32 v[44:45], v[44:45], s[0:1] op_sel_hi:[1,0]
	v_pk_mul_f32 v[52:53], v[42:43], s[0:1] op_sel_hi:[1,0]
	v_readlane_b32 s0, v253, 26
	v_readlane_b32 s1, v253, 27
	v_mov_b32_e32 v61, v60
	v_cvt_pk_bf16_f32 v52, v52, v53
	v_cvt_pk_bf16_f32 v53, v44, v45
	v_mov_b32_e32 v44, v60
	v_lshl_add_u64 v[42:43], s[0:1], 0, v[72:73]
	v_mov_b32_e32 v45, v60
	v_lshl_add_u64 v[72:73], v[42:43], 0, v[48:49]
	v_pk_mul_f32 v[40:41], v[40:41], v[44:45]
	v_pk_mul_f32 v[38:39], v[38:39], v[60:61]
	global_store_dwordx2 v[72:73], v[52:53], off
	s_and_saveexec_b64 s[0:1], vcc
	s_cbranch_execz .LBB0_878
	s_waitcnt vmcnt(3)
	v_mov_b32_e32 v72, v190
	v_mov_b32_e32 v73, v191
	v_mov_b32_e32 v74, v192
	v_mov_b32_e32 v75, v193
	v_pk_mul_f32 v[52:53], v[38:39], v[72:73] op_sel:[1,1] op_sel_hi:[0,1]
	v_pk_mul_f32 v[44:45], v[38:39], v[72:73] op_sel_hi:[1,0]
	v_pk_fma_f32 v[38:39], v[38:39], v[72:73], v[52:53] op_sel_hi:[1,0,1]
	s_nop 0
	v_mul_f32_e32 v38, v41, v75
	v_pk_fma_f32 v[72:73], v[40:41], v[74:75], v[38:39] op_sel_hi:[1,1,0] neg_lo:[0,0,1] neg_hi:[0,0,1]
	v_mul_f32_e32 v38, v40, v75
	v_pk_fma_f32 v[74:75], v[40:41], v[74:75], v[38:39] op_sel:[1,0,0] op_sel_hi:[0,1,0]
	v_sub_f32_e32 v38, v44, v52
	v_mov_b32_e32 v40, v72
	v_mov_b32_e32 v41, v74
.LBB0_878:
	s_or_b64 exec, exec, s[0:1]
	s_mov_b32 s0, 0x3e16c740
	v_pk_mul_f32 v[40:41], v[40:41], s[0:1] op_sel_hi:[1,0]
	v_pk_mul_f32 v[44:45], v[38:39], s[0:1] op_sel_hi:[1,0]
	v_readlane_b32 s0, v253, 26
	v_readlane_b32 s1, v253, 27
	v_mov_b32_e32 v59, v58
	v_mov_b32_e32 v49, v33
	v_lshl_add_u64 v[38:39], s[0:1], 0, v[56:57]
	v_cvt_pk_bf16_f32 v44, v44, v45
	v_cvt_pk_bf16_f32 v45, v40, v41
	v_mov_b32_e32 v40, v58
	v_mov_b32_e32 v41, v58
	v_lshl_add_u64 v[52:53], v[38:39], 0, v[48:49]
	v_pk_mul_f32 v[36:37], v[36:37], v[40:41]
	v_pk_mul_f32 v[34:35], v[34:35], v[58:59]
	global_store_dwordx2 v[52:53], v[44:45], off
	s_and_saveexec_b64 s[0:1], vcc
	s_cbranch_execz .LBB0_880
	s_waitcnt vmcnt(3)
	v_mov_b32_e32 v72, v194
	v_mov_b32_e32 v73, v195
	v_mov_b32_e32 v74, v196
	v_mov_b32_e32 v75, v197
	v_mul_f32_e32 v32, v37, v75
	v_pk_mul_f32 v[44:45], v[34:35], v[72:73] op_sel:[1,1] op_sel_hi:[0,1]
	v_pk_fma_f32 v[52:53], v[36:37], v[74:75], v[32:33] op_sel_hi:[1,1,0] neg_lo:[0,0,1] neg_hi:[0,0,1]
	v_mul_f32_e32 v32, v36, v75
	v_pk_mul_f32 v[40:41], v[34:35], v[72:73] op_sel_hi:[1,0]
	v_pk_fma_f32 v[34:35], v[34:35], v[72:73], v[44:45] op_sel_hi:[1,0,1]
	v_pk_fma_f32 v[56:57], v[36:37], v[74:75], v[32:33] op_sel:[1,0,0] op_sel_hi:[0,1,0]
	v_sub_f32_e32 v34, v40, v44
	v_mov_b32_e32 v36, v52
	v_mov_b32_e32 v37, v56
; DEVI void store_bf4(bf16_t* p, f32x4 v) { u32x2 w; w.x = pk2(v[0], v[1]); w.y = pk2(v[2], v[3]); *(u32x2*)p = w; }
;   DEVI void operator()(int m, int n, f32x4 v, float rs) const {
;     if (n >= 480) return;
;     v *= rs;
;     int d = n % 96;
;     if (d >= 64) {
;       const float4 cs = *(const float4*)(rope + ((size_t)m * 56 + 8 + ((d - 64) >> 1)) * 2);
;       float a0 = v[0] * cs.x - v[1] * cs.y, a1 = v[1] * cs.x + v[0] * cs.y;
;       float a2 = v[2] * cs.z - v[3] * cs.w, a3 = v[3] * cs.z + v[2] * cs.w;
;       v = (f32x4){a0, a1, a2, a3};
;     }
;     v *= QSCALE_MLA;
;     store_bf4(qm + (size_t)m * 512 + n, v);
.LBB0_880:
	s_or_b64 exec, exec, s[0:1]
	s_mov_b32 s0, 0x3e16c740
	v_pk_mul_f32 v[36:37], v[36:37], s[0:1] op_sel_hi:[1,0]
	v_pk_mul_f32 v[40:41], v[34:35], s[0:1] op_sel_hi:[1,0]
	v_readlane_b32 s0, v253, 26
	v_readlane_b32 s1, v253, 27
	v_cvt_pk_bf16_f32 v40, v40, v41
	v_cvt_pk_bf16_f32 v41, v36, v37
	s_nop 1
	v_lshl_add_u64 v[34:35], s[0:1], 0, v[50:51]
	s_movk_i32 s0, 0x1c0
	v_lshl_add_u64 v[44:45], v[34:35], 0, v[48:49]
	v_cmp_gt_u32_e32 vcc, s0, v78
	global_store_dwordx2 v[44:45], v[40:41], off
	s_and_saveexec_b64 s[0:1], vcc
	s_cbranch_execz .LBB0_890
	v_or_b32_e32 v32, 32, v78
	s_mov_b32 s2, 0x2aaaaab
	v_mul_hi_u32 v36, v32, s2
	v_mul_u32_u24_e32 v36, 0x60, v36
	v_sub_u32_e32 v36, v32, v36
	v_cmp_lt_u32_e32 vcc, 63, v36
	v_subrev_u32_e32 v36, 64, v36
	v_lshrrev_b32_e32 v36, 1, v36
	v_mov_b32_e32 v40, v66
	v_mov_b32_e32 v41, v66
	v_add_u32_e32 v36, 8, v36
	v_mov_b32_e32 v37, v33
	v_pk_mul_f32 v[30:31], v[30:31], v[40:41]
	v_pk_mul_f32 v[28:29], v[28:29], v[66:67]
	s_and_saveexec_b64 s[6:7], vcc
	v_readlane_b32 s2, v252, 63
	v_readlane_b32 s3, v253, 0
	v_mov_b32_e32 v198, v64
	v_mad_u32_u24 v198, v198, 56, v36
	v_lshlrev_b32_e32 v198, 3, v198
	v_or_b32_e32 v199, 16, v64
	v_mad_u32_u24 v199, v199, 56, v36
	v_lshlrev_b32_e32 v199, 3, v199
	v_or_b32_e32 v200, 32, v64
	v_mad_u32_u24 v200, v200, 56, v36
	v_lshlrev_b32_e32 v200, 3, v200
	v_or_b32_e32 v201, 48, v64
	v_mad_u32_u24 v201, v201, 56, v36
	v_lshlrev_b32_e32 v201, 3, v201
	global_load_dwordx4 v[182:185], v198, s[2:3]
	global_load_dwordx4 v[186:189], v199, s[2:3]
	global_load_dwordx4 v[190:193], v200, s[2:3]
	global_load_dwordx4 v[194:197], v201, s[2:3]
	s_or_b64 exec, exec, s[6:7]
	s_and_saveexec_b64 s[6:7], vcc
	s_cbranch_execz .LBB0_883
	s_waitcnt vmcnt(3)
	v_mov_b32_e32 v48, v182
	v_mov_b32_e32 v49, v183
	v_mov_b32_e32 v50, v184
	v_mov_b32_e32 v51, v185
	v_pk_mul_f32 v[44:45], v[28:29], v[48:49] op_sel:[1,1] op_sel_hi:[0,1]
	v_pk_mul_f32 v[40:41], v[28:29], v[48:49] op_sel_hi:[1,0]
	v_pk_fma_f32 v[28:29], v[28:29], v[48:49], v[44:45] op_sel_hi:[1,0,1]
	s_nop 0
	v_mul_f32_e32 v28, v31, v51
	v_pk_fma_f32 v[48:49], v[30:31], v[50:51], v[28:29] op_sel_hi:[1,1,0] neg_lo:[0,0,1] neg_hi:[0,0,1]
	v_mul_f32_e32 v28, v30, v51
	v_pk_fma_f32 v[50:51], v[30:31], v[50:51], v[28:29] op_sel:[1,0,0] op_sel_hi:[0,1,0]
	v_sub_f32_e32 v28, v40, v44
	v_mov_b32_e32 v30, v48
	v_mov_b32_e32 v31, v50
.LBB0_883:
	s_or_b64 exec, exec, s[6:7]
	s_mov_b32 s2, 0x3e16c740
	v_pk_mul_f32 v[28:29], v[28:29], s[2:3] op_sel_hi:[1,0]
	v_lshlrev_b32_e32 v32, 1, v32
	v_pk_mul_f32 v[30:31], v[30:31], s[2:3] op_sel_hi:[1,0]
	v_lshl_add_u64 v[40:41], v[46:47], 0, v[32:33]
	v_cvt_pk_bf16_f32 v28, v28, v29
	v_cvt_pk_bf16_f32 v29, v30, v31
	global_store_dwordx2 v[40:41], v[28:29], off
	v_mov_b32_e32 v28, v62
	v_mov_b32_e32 v29, v62
	v_pk_mul_f32 v[26:27], v[26:27], v[28:29]
	v_pk_mul_f32 v[24:25], v[24:25], v[62:63]
	s_and_saveexec_b64 s[6:7], vcc
	s_cbranch_execz .LBB0_885
	s_waitcnt vmcnt(3)
	v_mov_b32_e32 v28, v186
	v_mov_b32_e32 v29, v187
	v_mov_b32_e32 v30, v188
	v_mov_b32_e32 v31, v189
	v_pk_mul_f32 v[44:45], v[24:25], v[28:29] op_sel:[1,1] op_sel_hi:[0,1]
	v_pk_mul_f32 v[40:41], v[24:25], v[28:29] op_sel_hi:[1,0]
	v_pk_fma_f32 v[24:25], v[24:25], v[28:29], v[44:45] op_sel_hi:[1,0,1]
	s_nop 0
	v_mul_f32_e32 v24, v27, v31
	v_pk_fma_f32 v[28:29], v[26:27], v[30:31], v[24:25] op_sel_hi:[1,1,0] neg_lo:[0,0,1] neg_hi:[0,0,1]
	v_mul_f32_e32 v24, v26, v31
	v_pk_fma_f32 v[30:31], v[26:27], v[30:31], v[24:25] op_sel:[1,0,0] op_sel_hi:[0,1,0]
	v_sub_f32_e32 v24, v40, v44
	v_mov_b32_e32 v26, v28
	v_mov_b32_e32 v27, v30
.LBB0_885:
	s_or_b64 exec, exec, s[6:7]
	s_mov_b32 s2, 0x3e16c740
	v_pk_mul_f32 v[24:25], v[24:25], s[2:3] op_sel_hi:[1,0]
	v_pk_mul_f32 v[26:27], v[26:27], s[2:3] op_sel_hi:[1,0]
	v_lshl_add_u64 v[28:29], v[42:43], 0, v[32:33]
	v_cvt_pk_bf16_f32 v24, v24, v25
	v_cvt_pk_bf16_f32 v25, v26, v27
	global_store_dwordx2 v[28:29], v[24:25], off
	v_mov_b32_e32 v24, v60
	v_mov_b32_e32 v25, v60
	v_pk_mul_f32 v[22:23], v[22:23], v[24:25]
	v_pk_mul_f32 v[20:21], v[20:21], v[60:61]
	s_and_saveexec_b64 s[6:7], vcc
	s_cbranch_execz .LBB0_887
	s_waitcnt vmcnt(3)
	v_mov_b32_e32 v24, v190
	v_mov_b32_e32 v25, v191
	v_mov_b32_e32 v26, v192
	v_mov_b32_e32 v27, v193
	v_pk_mul_f32 v[30:31], v[20:21], v[24:25] op_sel:[1,1] op_sel_hi:[0,1]
	v_pk_mul_f32 v[28:29], v[20:21], v[24:25] op_sel_hi:[1,0]
	v_pk_fma_f32 v[20:21], v[20:21], v[24:25], v[30:31] op_sel_hi:[1,0,1]
	s_nop 0
	v_mul_f32_e32 v20, v23, v27
	v_pk_fma_f32 v[24:25], v[22:23], v[26:27], v[20:21] op_sel_hi:[1,1,0] neg_lo:[0,0,1] neg_hi:[0,0,1]
	v_mul_f32_e32 v20, v22, v27
	v_pk_fma_f32 v[26:27], v[22:23], v[26:27], v[20:21] op_sel:[1,0,0] op_sel_hi:[0,1,0]
	v_sub_f32_e32 v20, v28, v30
	v_mov_b32_e32 v22, v24
	v_mov_b32_e32 v23, v26
.LBB0_887:
	s_or_b64 exec, exec, s[6:7]
	s_mov_b32 s2, 0x3e16c740
	v_pk_mul_f32 v[20:21], v[20:21], s[2:3] op_sel_hi:[1,0]
	v_pk_mul_f32 v[22:23], v[22:23], s[2:3] op_sel_hi:[1,0]
	v_lshl_add_u64 v[24:25], v[38:39], 0, v[32:33]
	v_cvt_pk_bf16_f32 v20, v20, v21
	v_cvt_pk_bf16_f32 v21, v22, v23
	global_store_dwordx2 v[24:25], v[20:21], off
	v_mov_b32_e32 v20, v58
	v_mov_b32_e32 v21, v58
	v_pk_mul_f32 v[18:19], v[18:19], v[20:21]
	v_pk_mul_f32 v[16:17], v[16:17], v[58:59]
	s_and_saveexec_b64 s[6:7], vcc
	s_cbranch_execz .LBB0_889
	s_waitcnt vmcnt(3)
	v_mov_b32_e32 v20, v194
	v_mov_b32_e32 v21, v195
	v_mov_b32_e32 v22, v196
	v_mov_b32_e32 v23, v197
	v_pk_mul_f32 v[26:27], v[16:17], v[20:21] op_sel:[1,1] op_sel_hi:[0,1]
	v_pk_mul_f32 v[24:25], v[16:17], v[20:21] op_sel_hi:[1,0]
	v_pk_fma_f32 v[16:17], v[16:17], v[20:21], v[26:27] op_sel_hi:[1,0,1]
	s_nop 0
	v_mul_f32_e32 v16, v19, v23
	v_pk_fma_f32 v[20:21], v[18:19], v[22:23], v[16:17] op_sel_hi:[1,1,0] neg_lo:[0,0,1] neg_hi:[0,0,1]
	v_mul_f32_e32 v16, v18, v23
	v_pk_fma_f32 v[22:23], v[18:19], v[22:23], v[16:17] op_sel:[1,0,0] op_sel_hi:[0,1,0]
	v_sub_f32_e32 v16, v24, v26
	v_mov_b32_e32 v18, v20
	v_mov_b32_e32 v19, v22

; DEVI void store_bf4(bf16_t* p, f32x4 v) { u32x2 w; w.x = pk2(v[0], v[1]); w.y = pk2(v[2], v[3]); *(u32x2*)p = w; }
;   DEVI void operator()(int m, int n, f32x4 v, float rs) const {
;     if (n >= 480) return;
;     v *= rs;
;     int d = n % 96;
;     if (d >= 64) {
;       const float4 cs = *(const float4*)(rope + ((size_t)m * 56 + 8 + ((d - 64) >> 1)) * 2);
;       float a0 = v[0] * cs.x - v[1] * cs.y, a1 = v[1] * cs.x + v[0] * cs.y;
;       float a2 = v[2] * cs.z - v[3] * cs.w, a3 = v[3] * cs.z + v[2] * cs.w;
;       v = (f32x4){a0, a1, a2, a3};
;     }
;     v *= QSCALE_MLA;
;     store_bf4(qm + (size_t)m * 512 + n, v);
.LBB0_890:
	s_or_b64 exec, exec, s[0:1]
	s_movk_i32 s0, 0x1b0
	v_cmp_gt_u32_e32 vcc, s0, v78
	s_and_saveexec_b64 s[0:1], vcc
	s_cbranch_execz .LBB0_900
	v_or_b32_e32 v18, 48, v78
	s_mov_b32 s2, 0x2aaaaab
	v_mul_hi_u32 v16, v18, s2
	v_mul_u32_u24_e32 v16, 0x60, v16
	v_sub_u32_e32 v16, v18, v16
	v_cmp_lt_u32_e32 vcc, 63, v16
	v_subrev_u32_e32 v16, 64, v16
	v_lshrrev_b32_e32 v16, 1, v16
	v_mov_b32_e32 v20, v66
	v_mov_b32_e32 v21, v66
	v_add_u32_e32 v16, 8, v16
	v_mov_b32_e32 v17, v33
	v_pk_mul_f32 v[14:15], v[14:15], v[20:21]
	v_pk_mul_f32 v[12:13], v[12:13], v[66:67]
	s_and_saveexec_b64 s[6:7], vcc
	v_readlane_b32 s2, v252, 63
	v_readlane_b32 s3, v253, 0
	v_mov_b32_e32 v198, v64
	v_mad_u32_u24 v198, v198, 56, v16
	v_lshlrev_b32_e32 v198, 3, v198
	v_or_b32_e32 v199, 16, v64
	v_mad_u32_u24 v199, v199, 56, v16
	v_lshlrev_b32_e32 v199, 3, v199
	v_or_b32_e32 v200, 32, v64
	v_mad_u32_u24 v200, v200, 56, v16
	v_lshlrev_b32_e32 v200, 3, v200
	v_or_b32_e32 v201, 48, v64
	v_mad_u32_u24 v201, v201, 56, v16
	v_lshlrev_b32_e32 v201, 3, v201
	global_load_dwordx4 v[182:185], v198, s[2:3]
	global_load_dwordx4 v[186:189], v199, s[2:3]
	global_load_dwordx4 v[190:193], v200, s[2:3]
	global_load_dwordx4 v[194:197], v201, s[2:3]
	s_or_b64 exec, exec, s[6:7]
	s_and_saveexec_b64 s[6:7], vcc
	s_cbranch_execz .LBB0_893
	s_waitcnt vmcnt(3)
	v_mov_b32_e32 v20, v182
	v_mov_b32_e32 v21, v183
	v_mov_b32_e32 v22, v184
	v_mov_b32_e32 v23, v185
	v_pk_mul_f32 v[26:27], v[12:13], v[20:21] op_sel:[1,1] op_sel_hi:[0,1]
	v_pk_mul_f32 v[24:25], v[12:13], v[20:21] op_sel_hi:[1,0]
	v_pk_fma_f32 v[12:13], v[12:13], v[20:21], v[26:27] op_sel_hi:[1,0,1]
	s_nop 0
	v_mul_f32_e32 v12, v15, v23
	v_pk_fma_f32 v[20:21], v[14:15], v[22:23], v[12:13] op_sel_hi:[1,1,0] neg_lo:[0,0,1] neg_hi:[0,0,1]
	v_mul_f32_e32 v12, v14, v23
	v_pk_fma_f32 v[22:23], v[14:15], v[22:23], v[12:13] op_sel:[1,0,0] op_sel_hi:[0,1,0]
	v_sub_f32_e32 v12, v24, v26
	v_mov_b32_e32 v14, v20
	v_mov_b32_e32 v15, v22
.LBB0_893:
	s_or_b64 exec, exec, s[6:7]
	s_mov_b32 s2, 0x3e16c740
	v_pk_mul_f32 v[12:13], v[12:13], s[2:3] op_sel_hi:[1,0]
	v_lshlrev_b32_e32 v32, 1, v18
	v_pk_mul_f32 v[14:15], v[14:15], s[2:3] op_sel_hi:[1,0]
	v_lshl_add_u64 v[18:19], v[46:47], 0, v[32:33]
	v_cvt_pk_bf16_f32 v12, v12, v13
	v_cvt_pk_bf16_f32 v13, v14, v15
	global_store_dwordx2 v[18:19], v[12:13], off
	v_mov_b32_e32 v12, v62
	v_mov_b32_e32 v13, v62
	v_pk_mul_f32 v[10:11], v[10:11], v[12:13]
	v_pk_mul_f32 v[8:9], v[8:9], v[62:63]
	s_and_saveexec_b64 s[6:7], vcc
	s_cbranch_execz .LBB0_895
	s_waitcnt vmcnt(3)
	v_mov_b32_e32 v12, v186
	v_mov_b32_e32 v13, v187
	v_mov_b32_e32 v14, v188
	v_mov_b32_e32 v15, v189
	v_pk_mul_f32 v[20:21], v[8:9], v[12:13] op_sel:[1,1] op_sel_hi:[0,1]
	v_pk_mul_f32 v[18:19], v[8:9], v[12:13] op_sel_hi:[1,0]
	v_pk_fma_f32 v[8:9], v[8:9], v[12:13], v[20:21] op_sel_hi:[1,0,1]
	s_nop 0
	v_mul_f32_e32 v8, v11, v15
	v_pk_fma_f32 v[12:13], v[10:11], v[14:15], v[8:9] op_sel_hi:[1,1,0] neg_lo:[0,0,1] neg_hi:[0,0,1]
	v_mul_f32_e32 v8, v10, v15
	v_pk_fma_f32 v[14:15], v[10:11], v[14:15], v[8:9] op_sel:[1,0,0] op_sel_hi:[0,1,0]
	v_sub_f32_e32 v8, v18, v20
	v_mov_b32_e32 v10, v12
	v_mov_b32_e32 v11, v14
.LBB0_895:
	s_or_b64 exec, exec, s[6:7]
	s_mov_b32 s2, 0x3e16c740
	v_pk_mul_f32 v[8:9], v[8:9], s[2:3] op_sel_hi:[1,0]
	v_pk_mul_f32 v[10:11], v[10:11], s[2:3] op_sel_hi:[1,0]
	v_lshl_add_u64 v[12:13], v[42:43], 0, v[32:33]
	v_cvt_pk_bf16_f32 v8, v8, v9
	v_cvt_pk_bf16_f32 v9, v10, v11
	global_store_dwordx2 v[12:13], v[8:9], off
	v_mov_b32_e32 v8, v60
	v_mov_b32_e32 v9, v60
	v_pk_mul_f32 v[6:7], v[6:7], v[8:9]
	v_pk_mul_f32 v[4:5], v[4:5], v[60:61]
	s_and_saveexec_b64 s[6:7], vcc
	s_cbranch_execz .LBB0_897
	s_waitcnt vmcnt(3)
	v_mov_b32_e32 v8, v190
	v_mov_b32_e32 v9, v191
	v_mov_b32_e32 v10, v192
	v_mov_b32_e32 v11, v193
	v_pk_mul_f32 v[14:15], v[4:5], v[8:9] op_sel:[1,1] op_sel_hi:[0,1]
	v_pk_mul_f32 v[12:13], v[4:5], v[8:9] op_sel_hi:[1,0]
	v_pk_fma_f32 v[4:5], v[4:5], v[8:9], v[14:15] op_sel_hi:[1,0,1]
	s_nop 0
	v_mul_f32_e32 v4, v7, v11
	v_pk_fma_f32 v[8:9], v[6:7], v[10:11], v[4:5] op_sel_hi:[1,1,0] neg_lo:[0,0,1] neg_hi:[0,0,1]
	v_mul_f32_e32 v4, v6, v11
	v_pk_fma_f32 v[10:11], v[6:7], v[10:11], v[4:5] op_sel:[1,0,0] op_sel_hi:[0,1,0]
	v_sub_f32_e32 v4, v12, v14
	v_mov_b32_e32 v6, v8
	v_mov_b32_e32 v7, v10
.LBB0_897:
	s_or_b64 exec, exec, s[6:7]
	s_mov_b32 s2, 0x3e16c740
	v_pk_mul_f32 v[4:5], v[4:5], s[2:3] op_sel_hi:[1,0]
	v_pk_mul_f32 v[6:7], v[6:7], s[2:3] op_sel_hi:[1,0]
	v_lshl_add_u64 v[8:9], v[38:39], 0, v[32:33]
	v_cvt_pk_bf16_f32 v4, v4, v5
	v_cvt_pk_bf16_f32 v5, v6, v7
	global_store_dwordx2 v[8:9], v[4:5], off
	v_mov_b32_e32 v4, v58
	v_mov_b32_e32 v5, v58
	v_pk_mul_f32 v[2:3], v[2:3], v[4:5]
	v_pk_mul_f32 v[0:1], v[0:1], v[58:59]
	s_and_saveexec_b64 s[6:7], vcc
	s_cbranch_execz .LBB0_899
	s_waitcnt vmcnt(3)
	v_mov_b32_e32 v4, v194
	v_mov_b32_e32 v5, v195
	v_mov_b32_e32 v6, v196
	v_mov_b32_e32 v7, v197
	v_pk_mul_f32 v[10:11], v[0:1], v[4:5] op_sel:[1,1] op_sel_hi:[0,1]
	v_pk_mul_f32 v[8:9], v[0:1], v[4:5] op_sel_hi:[1,0]
	v_pk_fma_f32 v[0:1], v[0:1], v[4:5], v[10:11] op_sel_hi:[1,0,1]
	s_nop 0
	v_mul_f32_e32 v0, v3, v7
	v_pk_fma_f32 v[4:5], v[2:3], v[6:7], v[0:1] op_sel_hi:[1,1,0] neg_lo:[0,0,1] neg_hi:[0,0,1]
	v_mul_f32_e32 v0, v2, v7
	v_pk_fma_f32 v[6:7], v[2:3], v[6:7], v[0:1] op_sel:[1,0,0] op_sel_hi:[0,1,0]
	v_sub_f32_e32 v0, v8, v10
	v_mov_b32_e32 v2, v4
	v_mov_b32_e32 v3, v6
